# GLA scan: operand LDS reads issued before the pack, output-side LDS reads interleaved into the state-update MFMA chain
# speedup vs baseline: 1.0290x; 1.0141x over previous
.Lsc_lloop:
.Lsc_lbody0:
	ds_read_b128 v[128:131], v208 offset:0
	ds_read_b128 v[132:135], v208 offset:32
	ds_read_b128 v[136:139], v208 offset:64
	ds_read_b128 v[140:143], v208 offset:96
	ds_read_b128 v[96:99], v209 offset:0
	ds_read_b128 v[100:103], v209 offset:32
	ds_read_b128 v[104:107], v209 offset:64
	ds_read_b128 v[108:111], v209 offset:96
	ds_read_b128 v[112:115], v210 offset:0
	ds_read_b128 v[116:119], v210 offset:32
	ds_read_b128 v[120:123], v210 offset:64
	ds_read_b128 v[124:127], v210 offset:96
	global_load_dwordx4 v[24:27], v236, s[24:25] offset:-4096
	global_load_dwordx4 v[28:31], v236, s[24:25]
	global_load_dwordx4 v[32:35], v236, s[46:47] offset:-4096
	global_load_dwordx4 v[36:39], v236, s[46:47]
	global_load_dwordx4 v[40:43], v236, s[28:29] offset:-4096
	global_load_dwordx4 v[44:47], v236, s[28:29]
	global_load_dwordx4 v[48:51], v236, s[48:49] offset:-4096
	global_load_dwordx4 v[52:55], v236, s[48:49]
	global_load_dwordx4 v[56:59], v236, s[40:41] offset:-4096
	global_load_dwordx4 v[60:63], v236, s[40:41]
	global_load_dwordx4 v[64:67], v239, s[38:39]
	s_add_u32 s24, s24, 0x4000
	s_addc_u32 s25, s25, 0
	s_add_u32 s46, s46, 0x4000
	s_addc_u32 s47, s47, 0
	s_add_u32 s28, s28, 0x4000
	s_addc_u32 s29, s29, 0
	s_add_u32 s48, s48, 0x4000
	s_addc_u32 s49, s49, 0
	s_add_u32 s40, s40, 0x8000
	s_addc_u32 s41, s41, 0
	s_add_u32 s38, s38, 0x200
	s_addc_u32 s39, s39, 0
	v_cvt_pk_bf16_f32 v16, v0, v1
	v_cvt_pk_bf16_f32 v17, v2, v3
	v_cvt_pk_bf16_f32 v18, v4, v5
	v_cvt_pk_bf16_f32 v19, v6, v7
	v_cvt_pk_bf16_f32 v20, v8, v9
	v_cvt_pk_bf16_f32 v21, v10, v11
	v_cvt_pk_bf16_f32 v22, v12, v13
	v_cvt_pk_bf16_f32 v23, v14, v15
	s_waitcnt lgkmcnt(8)
	v_mul_f32_e32 v0, v0, v128
	v_mul_f32_e32 v1, v1, v129
	v_mul_f32_e32 v2, v2, v130
	v_mul_f32_e32 v3, v3, v131
	v_mul_f32_e32 v4, v4, v132
	v_mul_f32_e32 v5, v5, v133
	v_mul_f32_e32 v6, v6, v134
	v_mul_f32_e32 v7, v7, v135
	v_mul_f32_e32 v8, v8, v136
	v_mul_f32_e32 v9, v9, v137
	v_mul_f32_e32 v10, v10, v138
	v_mul_f32_e32 v11, v11, v139
	v_mul_f32_e32 v12, v12, v140
	v_mul_f32_e32 v13, v13, v141
	v_mul_f32_e32 v14, v14, v142
	v_mul_f32_e32 v15, v15, v143
	ds_write_b64 v164, v[16:17] offset:0
	ds_write_b64 v164, v[18:19] offset:16
	ds_write_b64 v164, v[20:21] offset:32
	ds_write_b64 v164, v[22:23] offset:48
	s_waitcnt lgkmcnt(4)
	v_mfma_f32_32x32x16_bf16 v[0:15], v[96:99], v[112:115], v[0:15]
	v_mfma_f32_32x32x16_bf16 v[0:15], v[100:103], v[116:119], v[0:15]
	v_mfma_f32_32x32x16_bf16 v[0:15], v[104:107], v[120:123], v[0:15]
	v_mfma_f32_32x32x16_bf16 v[0:15], v[108:111], v[124:127], v[0:15]
	s_waitcnt vmcnt(22)
	ds_write_b128 v237, v[68:71] offset:45568
	ds_write_b128 v237, v[72:75] offset:49920
	ds_write_b128 v237, v[76:79] offset:54272
	ds_write_b128 v237, v[80:83] offset:58624
	ds_write_b128 v238, v[84:87] offset:45568
	ds_write_b128 v238, v[88:91] offset:50176
	ds_write_b128 v238, v[92:95] offset:54784
	ds_write_b128 v238, v[144:147] offset:59392
	ds_write_b128 v166, v[148:151] offset:45568
	ds_write_b128 v166, v[152:155] offset:50176
	ds_write_b128 v239, v[156:159] offset:45568
	s_add_i32 s44, s44, 1
	s_waitcnt lgkmcnt(0)
	s_barrier
.Lsc_lbody1:
	ds_read_b128 v[128:131], v208 offset:45568
	ds_read_b128 v[132:135], v208 offset:45600
	ds_read_b128 v[136:139], v208 offset:45632
	ds_read_b128 v[140:143], v208 offset:45664
	ds_read_b128 v[96:99], v209 offset:45568
	ds_read_b128 v[100:103], v209 offset:45600
	ds_read_b128 v[104:107], v209 offset:45632
	ds_read_b128 v[108:111], v209 offset:45664
	ds_read_b128 v[112:115], v210 offset:45568
	ds_read_b128 v[116:119], v210 offset:45600
	ds_read_b128 v[120:123], v210 offset:45632
	ds_read_b128 v[124:127], v210 offset:45664
	s_cmp_lt_u32 s44, 61
	s_cbranch_scc0 .Lsc_nold_lk1
	global_load_dwordx4 v[68:71], v236, s[24:25] offset:-4096
	global_load_dwordx4 v[72:75], v236, s[24:25]
	global_load_dwordx4 v[76:79], v236, s[46:47] offset:-4096
	global_load_dwordx4 v[80:83], v236, s[46:47]
	global_load_dwordx4 v[84:87], v236, s[28:29] offset:-4096
	global_load_dwordx4 v[88:91], v236, s[28:29]
	global_load_dwordx4 v[92:95], v236, s[48:49] offset:-4096
	global_load_dwordx4 v[144:147], v236, s[48:49]
	global_load_dwordx4 v[148:151], v236, s[40:41] offset:-4096
	global_load_dwordx4 v[152:155], v236, s[40:41]
	global_load_dwordx4 v[156:159], v239, s[38:39]
	s_add_u32 s24, s24, 0x4000
	s_addc_u32 s25, s25, 0
	s_add_u32 s46, s46, 0x4000
	s_addc_u32 s47, s47, 0
	s_add_u32 s28, s28, 0x4000
	s_addc_u32 s29, s29, 0
	s_add_u32 s48, s48, 0x4000
	s_addc_u32 s49, s49, 0
	s_add_u32 s40, s40, 0x8000
	s_addc_u32 s41, s41, 0
	s_add_u32 s38, s38, 0x200
	s_addc_u32 s39, s39, 0
.Lsc_nold_lk1:
	v_cvt_pk_bf16_f32 v16, v0, v1
	v_cvt_pk_bf16_f32 v17, v2, v3
	v_cvt_pk_bf16_f32 v18, v4, v5
	v_cvt_pk_bf16_f32 v19, v6, v7
	v_cvt_pk_bf16_f32 v20, v8, v9
	v_cvt_pk_bf16_f32 v21, v10, v11
	v_cvt_pk_bf16_f32 v22, v12, v13
	v_cvt_pk_bf16_f32 v23, v14, v15
	s_waitcnt lgkmcnt(8)
	v_mul_f32_e32 v0, v0, v128
	v_mul_f32_e32 v1, v1, v129
	v_mul_f32_e32 v2, v2, v130
	v_mul_f32_e32 v3, v3, v131
	v_mul_f32_e32 v4, v4, v132
	v_mul_f32_e32 v5, v5, v133
	v_mul_f32_e32 v6, v6, v134
	v_mul_f32_e32 v7, v7, v135
	v_mul_f32_e32 v8, v8, v136
	v_mul_f32_e32 v9, v9, v137
	v_mul_f32_e32 v10, v10, v138
	v_mul_f32_e32 v11, v11, v139
	v_mul_f32_e32 v12, v12, v140
	v_mul_f32_e32 v13, v13, v141
	v_mul_f32_e32 v14, v14, v142
	v_mul_f32_e32 v15, v15, v143
	ds_write_b64 v164, v[16:17] offset:17408
	ds_write_b64 v164, v[18:19] offset:17424
	ds_write_b64 v164, v[20:21] offset:17440
	ds_write_b64 v164, v[22:23] offset:17456
	s_waitcnt lgkmcnt(4)
	v_mfma_f32_32x32x16_bf16 v[0:15], v[96:99], v[112:115], v[0:15]
	v_mfma_f32_32x32x16_bf16 v[0:15], v[100:103], v[116:119], v[0:15]
	v_mfma_f32_32x32x16_bf16 v[0:15], v[104:107], v[120:123], v[0:15]
	v_mfma_f32_32x32x16_bf16 v[0:15], v[108:111], v[124:127], v[0:15]
	s_cmp_lt_u32 s44, 61
	s_cbranch_scc1 .Lsc_w22_lk1
	s_waitcnt vmcnt(0)
	s_branch .Lsc_wd_lk1

.Lsc_lbody2:
	ds_read_b128 v[128:131], v208 offset:0
	ds_read_b128 v[132:135], v208 offset:32
	ds_read_b128 v[136:139], v208 offset:64
	ds_read_b128 v[140:143], v208 offset:96
	ds_read_b128 v[96:99], v209 offset:0
	ds_read_b128 v[100:103], v209 offset:32
	ds_read_b128 v[104:107], v209 offset:64
	ds_read_b128 v[108:111], v209 offset:96
	ds_read_b128 v[112:115], v210 offset:0
	ds_read_b128 v[116:119], v210 offset:32
	ds_read_b128 v[120:123], v210 offset:64
	ds_read_b128 v[124:127], v210 offset:96
	s_cmp_lt_u32 s44, 61
	s_cbranch_scc0 .Lsc_nold_lk2
	global_load_dwordx4 v[160:163], v236, s[24:25] offset:-4096
	global_load_dwordx4 v[172:175], v236, s[24:25]
	global_load_dwordx4 v[180:183], v236, s[46:47] offset:-4096
	global_load_dwordx4 v[184:187], v236, s[46:47]
	global_load_dwordx4 v[188:191], v236, s[28:29] offset:-4096
	global_load_dwordx4 v[192:195], v236, s[28:29]
	global_load_dwordx4 v[196:199], v236, s[48:49] offset:-4096
	global_load_dwordx4 v[200:203], v236, s[48:49]
	global_load_dwordx4 v[204:207], v236, s[40:41] offset:-4096
	global_load_dwordx4 v[212:215], v236, s[40:41]
	global_load_dwordx4 v[216:219], v239, s[38:39]
	s_add_u32 s24, s24, 0x4000
	s_addc_u32 s25, s25, 0
	s_add_u32 s46, s46, 0x4000
	s_addc_u32 s47, s47, 0
	s_add_u32 s28, s28, 0x4000
	s_addc_u32 s29, s29, 0
	s_add_u32 s48, s48, 0x4000
	s_addc_u32 s49, s49, 0
	s_add_u32 s40, s40, 0x8000
	s_addc_u32 s41, s41, 0
	s_add_u32 s38, s38, 0x200
	s_addc_u32 s39, s39, 0
.Lsc_nold_lk2:
	v_cvt_pk_bf16_f32 v16, v0, v1
	v_cvt_pk_bf16_f32 v17, v2, v3
	v_cvt_pk_bf16_f32 v18, v4, v5
	v_cvt_pk_bf16_f32 v19, v6, v7
	v_cvt_pk_bf16_f32 v20, v8, v9
	v_cvt_pk_bf16_f32 v21, v10, v11
	v_cvt_pk_bf16_f32 v22, v12, v13
	v_cvt_pk_bf16_f32 v23, v14, v15
	s_waitcnt lgkmcnt(8)
	v_mul_f32_e32 v0, v0, v128
	v_mul_f32_e32 v1, v1, v129
	v_mul_f32_e32 v2, v2, v130
	v_mul_f32_e32 v3, v3, v131
	v_mul_f32_e32 v4, v4, v132
	v_mul_f32_e32 v5, v5, v133
	v_mul_f32_e32 v6, v6, v134
	v_mul_f32_e32 v7, v7, v135
	v_mul_f32_e32 v8, v8, v136
	v_mul_f32_e32 v9, v9, v137
	v_mul_f32_e32 v10, v10, v138
	v_mul_f32_e32 v11, v11, v139
	v_mul_f32_e32 v12, v12, v140
	v_mul_f32_e32 v13, v13, v141
	v_mul_f32_e32 v14, v14, v142
	v_mul_f32_e32 v15, v15, v143
	ds_write_b64 v164, v[16:17] offset:0
	ds_write_b64 v164, v[18:19] offset:16
	ds_write_b64 v164, v[20:21] offset:32
	ds_write_b64 v164, v[22:23] offset:48
	s_waitcnt lgkmcnt(4)
	v_mfma_f32_32x32x16_bf16 v[0:15], v[96:99], v[112:115], v[0:15]
	v_mfma_f32_32x32x16_bf16 v[0:15], v[100:103], v[116:119], v[0:15]
	v_mfma_f32_32x32x16_bf16 v[0:15], v[104:107], v[120:123], v[0:15]
	v_mfma_f32_32x32x16_bf16 v[0:15], v[108:111], v[124:127], v[0:15]
	s_cmp_lt_u32 s44, 61
	s_cbranch_scc1 .Lsc_w22_lk2
	s_waitcnt vmcnt(0)
	s_branch .Lsc_wd_lk2

.Lsc_lbody3:
	ds_read_b128 v[128:131], v208 offset:45568
	ds_read_b128 v[132:135], v208 offset:45600
	ds_read_b128 v[136:139], v208 offset:45632
	ds_read_b128 v[140:143], v208 offset:45664
	ds_read_b128 v[96:99], v209 offset:45568
	ds_read_b128 v[100:103], v209 offset:45600
	ds_read_b128 v[104:107], v209 offset:45632
	ds_read_b128 v[108:111], v209 offset:45664
	ds_read_b128 v[112:115], v210 offset:45568
	ds_read_b128 v[116:119], v210 offset:45600
	ds_read_b128 v[120:123], v210 offset:45632
	ds_read_b128 v[124:127], v210 offset:45664
	s_cmp_lt_u32 s44, 61
	s_cbranch_scc0 .Lsc_nold_lk3
	global_load_dwordx4 v[24:27], v236, s[24:25] offset:-4096
	global_load_dwordx4 v[28:31], v236, s[24:25]
	global_load_dwordx4 v[32:35], v236, s[46:47] offset:-4096
	global_load_dwordx4 v[36:39], v236, s[46:47]
	global_load_dwordx4 v[40:43], v236, s[28:29] offset:-4096
	global_load_dwordx4 v[44:47], v236, s[28:29]
	global_load_dwordx4 v[48:51], v236, s[48:49] offset:-4096
	global_load_dwordx4 v[52:55], v236, s[48:49]
	global_load_dwordx4 v[56:59], v236, s[40:41] offset:-4096
	global_load_dwordx4 v[60:63], v236, s[40:41]
	global_load_dwordx4 v[64:67], v239, s[38:39]
	s_add_u32 s24, s24, 0x4000
	s_addc_u32 s25, s25, 0
	s_add_u32 s46, s46, 0x4000
	s_addc_u32 s47, s47, 0
	s_add_u32 s28, s28, 0x4000
	s_addc_u32 s29, s29, 0
	s_add_u32 s48, s48, 0x4000
	s_addc_u32 s49, s49, 0
	s_add_u32 s40, s40, 0x8000
	s_addc_u32 s41, s41, 0
	s_add_u32 s38, s38, 0x200
	s_addc_u32 s39, s39, 0
.Lsc_nold_lk3:
	v_cvt_pk_bf16_f32 v16, v0, v1
	v_cvt_pk_bf16_f32 v17, v2, v3
	v_cvt_pk_bf16_f32 v18, v4, v5
	v_cvt_pk_bf16_f32 v19, v6, v7
	v_cvt_pk_bf16_f32 v20, v8, v9
	v_cvt_pk_bf16_f32 v21, v10, v11
	v_cvt_pk_bf16_f32 v22, v12, v13
	v_cvt_pk_bf16_f32 v23, v14, v15
	s_waitcnt lgkmcnt(8)
	v_mul_f32_e32 v0, v0, v128
	v_mul_f32_e32 v1, v1, v129
	v_mul_f32_e32 v2, v2, v130
	v_mul_f32_e32 v3, v3, v131
	v_mul_f32_e32 v4, v4, v132
	v_mul_f32_e32 v5, v5, v133
	v_mul_f32_e32 v6, v6, v134
	v_mul_f32_e32 v7, v7, v135
	v_mul_f32_e32 v8, v8, v136
	v_mul_f32_e32 v9, v9, v137
	v_mul_f32_e32 v10, v10, v138
	v_mul_f32_e32 v11, v11, v139
	v_mul_f32_e32 v12, v12, v140
	v_mul_f32_e32 v13, v13, v141
	v_mul_f32_e32 v14, v14, v142
	v_mul_f32_e32 v15, v15, v143
	ds_write_b64 v164, v[16:17] offset:17408
	ds_write_b64 v164, v[18:19] offset:17424
	ds_write_b64 v164, v[20:21] offset:17440
	ds_write_b64 v164, v[22:23] offset:17456
	s_waitcnt lgkmcnt(4)
	v_mfma_f32_32x32x16_bf16 v[0:15], v[96:99], v[112:115], v[0:15]
	v_mfma_f32_32x32x16_bf16 v[0:15], v[100:103], v[116:119], v[0:15]
	v_mfma_f32_32x32x16_bf16 v[0:15], v[104:107], v[120:123], v[0:15]
	v_mfma_f32_32x32x16_bf16 v[0:15], v[108:111], v[124:127], v[0:15]
	s_cmp_lt_u32 s44, 63
	s_cbranch_scc0 .Lsc_nostage_lk3
	s_cmp_lt_u32 s44, 61
	s_cbranch_scc1 .Lsc_w22_lk3
	s_waitcnt vmcnt(0)
	s_branch .Lsc_wd_lk3

.Lsc_lbody4:
	ds_read_b128 v[128:131], v208 offset:0
	ds_read_b128 v[132:135], v208 offset:32
	ds_read_b128 v[136:139], v208 offset:64
	ds_read_b128 v[140:143], v208 offset:96
	ds_read_b128 v[96:99], v209 offset:0
	ds_read_b128 v[100:103], v209 offset:32
	ds_read_b128 v[104:107], v209 offset:64
	ds_read_b128 v[108:111], v209 offset:96
	ds_read_b128 v[112:115], v210 offset:0
	ds_read_b128 v[116:119], v210 offset:32
	ds_read_b128 v[120:123], v210 offset:64
	ds_read_b128 v[124:127], v210 offset:96
	global_load_dwordx4 v[68:71], v236, s[24:25] offset:-4096
	global_load_dwordx4 v[72:75], v236, s[24:25]
	global_load_dwordx4 v[76:79], v236, s[46:47] offset:-4096
	global_load_dwordx4 v[80:83], v236, s[46:47]
	global_load_dwordx4 v[84:87], v236, s[28:29] offset:-4096
	global_load_dwordx4 v[88:91], v236, s[28:29]
	global_load_dwordx4 v[92:95], v236, s[48:49] offset:-4096
	global_load_dwordx4 v[144:147], v236, s[48:49]
	global_load_dwordx4 v[148:151], v236, s[40:41] offset:-4096
	global_load_dwordx4 v[152:155], v236, s[40:41]
	global_load_dwordx4 v[156:159], v239, s[38:39]
	s_add_u32 s24, s24, 0x4000
	s_addc_u32 s25, s25, 0
	s_add_u32 s46, s46, 0x4000
	s_addc_u32 s47, s47, 0
	s_add_u32 s28, s28, 0x4000
	s_addc_u32 s29, s29, 0
	s_add_u32 s48, s48, 0x4000
	s_addc_u32 s49, s49, 0
	s_add_u32 s40, s40, 0x8000
	s_addc_u32 s41, s41, 0
	s_add_u32 s38, s38, 0x200
	s_addc_u32 s39, s39, 0
	v_cvt_pk_bf16_f32 v16, v0, v1
	v_cvt_pk_bf16_f32 v17, v2, v3
	v_cvt_pk_bf16_f32 v18, v4, v5
	v_cvt_pk_bf16_f32 v19, v6, v7
	v_cvt_pk_bf16_f32 v20, v8, v9
	v_cvt_pk_bf16_f32 v21, v10, v11
	v_cvt_pk_bf16_f32 v22, v12, v13
	v_cvt_pk_bf16_f32 v23, v14, v15
	s_waitcnt lgkmcnt(8)
	v_mul_f32_e32 v0, v0, v128
	v_mul_f32_e32 v1, v1, v129
	v_mul_f32_e32 v2, v2, v130
	v_mul_f32_e32 v3, v3, v131
	v_mul_f32_e32 v4, v4, v132
	v_mul_f32_e32 v5, v5, v133
	v_mul_f32_e32 v6, v6, v134
	v_mul_f32_e32 v7, v7, v135
	v_mul_f32_e32 v8, v8, v136
	v_mul_f32_e32 v9, v9, v137
	v_mul_f32_e32 v10, v10, v138
	v_mul_f32_e32 v11, v11, v139
	v_mul_f32_e32 v12, v12, v140
	v_mul_f32_e32 v13, v13, v141
	v_mul_f32_e32 v14, v14, v142
	v_mul_f32_e32 v15, v15, v143
	ds_write_b64 v164, v[16:17] offset:0
	ds_write_b64 v164, v[18:19] offset:16
	ds_write_b64 v164, v[20:21] offset:32
	ds_write_b64 v164, v[22:23] offset:48
	s_waitcnt lgkmcnt(4)
	v_mfma_f32_32x32x16_bf16 v[0:15], v[96:99], v[112:115], v[0:15]
	v_mfma_f32_32x32x16_bf16 v[0:15], v[100:103], v[116:119], v[0:15]
	v_mfma_f32_32x32x16_bf16 v[0:15], v[104:107], v[120:123], v[0:15]
	v_mfma_f32_32x32x16_bf16 v[0:15], v[108:111], v[124:127], v[0:15]
	s_waitcnt vmcnt(22)
	ds_write_b128 v237, v[160:163] offset:45568
	ds_write_b128 v237, v[172:175] offset:49920
	ds_write_b128 v237, v[180:183] offset:54272
	ds_write_b128 v237, v[184:187] offset:58624
	ds_write_b128 v238, v[188:191] offset:45568
	ds_write_b128 v238, v[192:195] offset:50176
	ds_write_b128 v238, v[196:199] offset:54784
	ds_write_b128 v238, v[200:203] offset:59392
	ds_write_b128 v166, v[204:207] offset:45568
	ds_write_b128 v166, v[212:215] offset:50176
	ds_write_b128 v239, v[216:219] offset:45568
	s_add_i32 s44, s44, 1
	s_waitcnt lgkmcnt(0)
	s_barrier
.Lsc_lbody5:
	ds_read_b128 v[128:131], v208 offset:45568
	ds_read_b128 v[132:135], v208 offset:45600
	ds_read_b128 v[136:139], v208 offset:45632
	ds_read_b128 v[140:143], v208 offset:45664
	ds_read_b128 v[96:99], v209 offset:45568
	ds_read_b128 v[100:103], v209 offset:45600
	ds_read_b128 v[104:107], v209 offset:45632
	ds_read_b128 v[108:111], v209 offset:45664
	ds_read_b128 v[112:115], v210 offset:45568
	ds_read_b128 v[116:119], v210 offset:45600
	ds_read_b128 v[120:123], v210 offset:45632
	ds_read_b128 v[124:127], v210 offset:45664
	global_load_dwordx4 v[160:163], v236, s[24:25] offset:-4096
	global_load_dwordx4 v[172:175], v236, s[24:25]
	global_load_dwordx4 v[180:183], v236, s[46:47] offset:-4096
	global_load_dwordx4 v[184:187], v236, s[46:47]
	global_load_dwordx4 v[188:191], v236, s[28:29] offset:-4096
	global_load_dwordx4 v[192:195], v236, s[28:29]
	global_load_dwordx4 v[196:199], v236, s[48:49] offset:-4096
	global_load_dwordx4 v[200:203], v236, s[48:49]
	global_load_dwordx4 v[204:207], v236, s[40:41] offset:-4096
	global_load_dwordx4 v[212:215], v236, s[40:41]
	global_load_dwordx4 v[216:219], v239, s[38:39]
	s_add_u32 s24, s24, 0x4000
	s_addc_u32 s25, s25, 0
	s_add_u32 s46, s46, 0x4000
	s_addc_u32 s47, s47, 0
	s_add_u32 s28, s28, 0x4000
	s_addc_u32 s29, s29, 0
	s_add_u32 s48, s48, 0x4000
	s_addc_u32 s49, s49, 0
	s_add_u32 s40, s40, 0x8000
	s_addc_u32 s41, s41, 0
	s_add_u32 s38, s38, 0x200
	s_addc_u32 s39, s39, 0
	v_cvt_pk_bf16_f32 v16, v0, v1
	v_cvt_pk_bf16_f32 v17, v2, v3
	v_cvt_pk_bf16_f32 v18, v4, v5
	v_cvt_pk_bf16_f32 v19, v6, v7
	v_cvt_pk_bf16_f32 v20, v8, v9
	v_cvt_pk_bf16_f32 v21, v10, v11
	v_cvt_pk_bf16_f32 v22, v12, v13
	v_cvt_pk_bf16_f32 v23, v14, v15
	s_waitcnt lgkmcnt(8)
	v_mul_f32_e32 v0, v0, v128
	v_mul_f32_e32 v1, v1, v129
	v_mul_f32_e32 v2, v2, v130
	v_mul_f32_e32 v3, v3, v131
	v_mul_f32_e32 v4, v4, v132
	v_mul_f32_e32 v5, v5, v133
	v_mul_f32_e32 v6, v6, v134
	v_mul_f32_e32 v7, v7, v135
	v_mul_f32_e32 v8, v8, v136
	v_mul_f32_e32 v9, v9, v137
	v_mul_f32_e32 v10, v10, v138
	v_mul_f32_e32 v11, v11, v139
	v_mul_f32_e32 v12, v12, v140
	v_mul_f32_e32 v13, v13, v141
	v_mul_f32_e32 v14, v14, v142
	v_mul_f32_e32 v15, v15, v143
	ds_write_b64 v164, v[16:17] offset:17408
	ds_write_b64 v164, v[18:19] offset:17424
	ds_write_b64 v164, v[20:21] offset:17440
	ds_write_b64 v164, v[22:23] offset:17456
	s_waitcnt lgkmcnt(4)
	v_mfma_f32_32x32x16_bf16 v[0:15], v[96:99], v[112:115], v[0:15]
	v_mfma_f32_32x32x16_bf16 v[0:15], v[100:103], v[116:119], v[0:15]
	v_mfma_f32_32x32x16_bf16 v[0:15], v[104:107], v[120:123], v[0:15]
	v_mfma_f32_32x32x16_bf16 v[0:15], v[108:111], v[124:127], v[0:15]
	s_waitcnt vmcnt(22)
	ds_write_b128 v237, v[24:27] offset:0
	ds_write_b128 v237, v[28:31] offset:4352
	ds_write_b128 v237, v[32:35] offset:8704
	ds_write_b128 v237, v[36:39] offset:13056
	ds_write_b128 v238, v[40:43] offset:0
	ds_write_b128 v238, v[44:47] offset:4608
	ds_write_b128 v238, v[48:51] offset:9216
	ds_write_b128 v238, v[52:55] offset:13824
	ds_write_b128 v166, v[56:59] offset:0
	ds_write_b128 v166, v[60:63] offset:4608
	ds_write_b128 v239, v[64:67] offset:0
	s_add_i32 s44, s44, 1
	s_waitcnt lgkmcnt(0)
	s_barrier
	s_branch .Lsc_lloop

.Lsc_oloop:
.Lsc_obody0:
	ds_read_b128 v[128:131], v208 offset:0
	ds_read_b128 v[132:135], v208 offset:32
	ds_read_b128 v[136:139], v208 offset:64
	ds_read_b128 v[140:143], v208 offset:96
	ds_read_b128 v[96:99], v209 offset:0
	ds_read_b128 v[100:103], v209 offset:32
	ds_read_b128 v[104:107], v209 offset:64
	ds_read_b128 v[108:111], v209 offset:96
	ds_read_b128 v[112:115], v210 offset:0
	ds_read_b128 v[116:119], v210 offset:32
	ds_read_b128 v[120:123], v210 offset:64
	ds_read_b128 v[124:127], v210 offset:96
	v_cvt_pk_bf16_f32 v16, v0, v1
	v_cvt_pk_bf16_f32 v17, v2, v3
	v_cvt_pk_bf16_f32 v18, v4, v5
	v_cvt_pk_bf16_f32 v19, v6, v7
	v_cvt_pk_bf16_f32 v20, v8, v9
	v_cvt_pk_bf16_f32 v21, v10, v11
	v_cvt_pk_bf16_f32 v22, v12, v13
	v_cvt_pk_bf16_f32 v23, v14, v15
	s_waitcnt lgkmcnt(8)
	v_mul_f32_e32 v0, v0, v128
	v_mul_f32_e32 v1, v1, v129
	v_mul_f32_e32 v2, v2, v130
	v_mul_f32_e32 v3, v3, v131
	v_mul_f32_e32 v4, v4, v132
	v_mul_f32_e32 v5, v5, v133
	v_mul_f32_e32 v6, v6, v134
	v_mul_f32_e32 v7, v7, v135
	v_mul_f32_e32 v8, v8, v136
	v_mul_f32_e32 v9, v9, v137
	v_mul_f32_e32 v10, v10, v138
	v_mul_f32_e32 v11, v11, v139
	v_mul_f32_e32 v12, v12, v140
	v_mul_f32_e32 v13, v13, v141
	v_mul_f32_e32 v14, v14, v142
	v_mul_f32_e32 v15, v15, v143
	s_waitcnt lgkmcnt(0)
	s_nop 1
	v_mfma_f32_32x32x16_bf16 v[0:15], v[96:99], v[112:115], v[0:15]
	ds_read_b128 v[40:43], v89 offset:17408
	ds_read_b128 v[44:47], v89 offset:17472
	ds_read_b128 v[48:51], v89 offset:17536
	ds_read_b128 v[52:55], v89 offset:17600
	v_mfma_f32_32x32x16_bf16 v[0:15], v[100:103], v[116:119], v[0:15]
	ds_read_b128 v[128:131], v89 offset:18496
	ds_read_b128 v[132:135], v89 offset:18560
	ds_read_b128 v[136:139], v89 offset:18624
	ds_read_b128 v[140:143], v89 offset:18688
	v_mfma_f32_32x32x16_bf16 v[0:15], v[104:107], v[120:123], v[0:15]
	ds_write_b64 v164, v[16:17] offset:0
	ds_write_b64 v164, v[18:19] offset:16
	ds_write_b64 v164, v[20:21] offset:32
	ds_write_b64 v164, v[22:23] offset:48
	v_mfma_f32_32x32x16_bf16 v[0:15], v[108:111], v[124:127], v[0:15]
	s_waitcnt lgkmcnt(8)
	v_mfma_f32_16x16x32_bf16 v[24:27], v[40:43], v[72:75], 0
	v_mfma_f32_16x16x32_bf16 v[24:27], v[44:47], v[76:79], v[24:27]
	v_mfma_f32_16x16x32_bf16 v[24:27], v[48:51], v[80:83], v[24:27]
	v_mfma_f32_16x16x32_bf16 v[24:27], v[52:55], v[84:87], v[24:27]
	ds_read_b128 v[40:43], v89 offset:26112
	ds_read_b128 v[44:47], v89 offset:26176
	ds_read_b128 v[48:51], v89 offset:26240
	ds_read_b128 v[52:55], v89 offset:26304
	s_waitcnt lgkmcnt(8)
	v_mfma_f32_16x16x32_bf16 v[28:31], v[128:131], v[72:75], 0
	v_mfma_f32_16x16x32_bf16 v[28:31], v[132:135], v[76:79], v[28:31]
	v_mfma_f32_16x16x32_bf16 v[28:31], v[136:139], v[80:83], v[28:31]
	v_mfma_f32_16x16x32_bf16 v[28:31], v[140:143], v[84:87], v[28:31]
	ds_read_b128 v[128:131], v89 offset:27200
	ds_read_b128 v[132:135], v89 offset:27264
	ds_read_b128 v[136:139], v89 offset:27328
	ds_read_b128 v[140:143], v89 offset:27392
	s_waitcnt lgkmcnt(4)
	v_mfma_f32_16x16x32_bf16 v[32:35], v[40:43], v[72:75], 0
	v_mfma_f32_16x16x32_bf16 v[32:35], v[44:47], v[76:79], v[32:35]
	v_mfma_f32_16x16x32_bf16 v[32:35], v[48:51], v[80:83], v[32:35]
	v_mfma_f32_16x16x32_bf16 v[32:35], v[52:55], v[84:87], v[32:35]
	ds_read_b128 v[56:59], v88 offset:0
	ds_read_b128 v[60:63], v88 offset:64
	ds_read_b128 v[64:67], v88 offset:128
	ds_read_b128 v[68:71], v88 offset:192
	s_waitcnt lgkmcnt(4)
	v_mfma_f32_16x16x32_bf16 v[36:39], v[128:131], v[72:75], 0
	v_mfma_f32_16x16x32_bf16 v[36:39], v[132:135], v[76:79], v[36:39]
	v_mfma_f32_16x16x32_bf16 v[36:39], v[136:139], v[80:83], v[36:39]
	v_mfma_f32_16x16x32_bf16 v[36:39], v[140:143], v[84:87], v[36:39]
	s_cmp_eq_u32 s44, 0
	s_cbranch_scc1 .Lsc_nost_ok0
	v_cvt_pk_bf16_f32 v24, v24, v25
	v_cvt_pk_bf16_f32 v25, v26, v27
	v_cvt_pk_bf16_f32 v26, v28, v29
	v_cvt_pk_bf16_f32 v27, v30, v31
	global_store_dwordx4 v90, v[24:27], s[42:43]
	v_cvt_pk_bf16_f32 v32, v32, v33
	v_cvt_pk_bf16_f32 v33, v34, v35
	s_nop 1
	v_cvt_pk_bf16_f32 v34, v36, v37
	v_cvt_pk_bf16_f32 v35, v38, v39
	global_store_dwordx4 v90, v[32:35], s[42:43] offset:64
	s_add_u32 s42, s42, 0x68000
	s_addc_u32 s43, s43, 0

.Lsc_obody1:
	ds_read_b128 v[128:131], v208 offset:45568
	ds_read_b128 v[132:135], v208 offset:45600
	ds_read_b128 v[136:139], v208 offset:45632
	ds_read_b128 v[140:143], v208 offset:45664
	ds_read_b128 v[96:99], v209 offset:45568
	ds_read_b128 v[100:103], v209 offset:45600
	ds_read_b128 v[104:107], v209 offset:45632
	ds_read_b128 v[108:111], v209 offset:45664
	ds_read_b128 v[112:115], v210 offset:45568
	ds_read_b128 v[116:119], v210 offset:45600
	ds_read_b128 v[120:123], v210 offset:45632
	ds_read_b128 v[124:127], v210 offset:45664
	v_cvt_pk_bf16_f32 v16, v0, v1
	v_cvt_pk_bf16_f32 v17, v2, v3
	v_cvt_pk_bf16_f32 v18, v4, v5
	v_cvt_pk_bf16_f32 v19, v6, v7
	v_cvt_pk_bf16_f32 v20, v8, v9
	v_cvt_pk_bf16_f32 v21, v10, v11
	v_cvt_pk_bf16_f32 v22, v12, v13
	v_cvt_pk_bf16_f32 v23, v14, v15
	s_waitcnt lgkmcnt(8)
	v_mul_f32_e32 v0, v0, v128
	v_mul_f32_e32 v1, v1, v129
	v_mul_f32_e32 v2, v2, v130
	v_mul_f32_e32 v3, v3, v131
	v_mul_f32_e32 v4, v4, v132
	v_mul_f32_e32 v5, v5, v133
	v_mul_f32_e32 v6, v6, v134
	v_mul_f32_e32 v7, v7, v135
	v_mul_f32_e32 v8, v8, v136
	v_mul_f32_e32 v9, v9, v137
	v_mul_f32_e32 v10, v10, v138
	v_mul_f32_e32 v11, v11, v139
	v_mul_f32_e32 v12, v12, v140
	v_mul_f32_e32 v13, v13, v141
	v_mul_f32_e32 v14, v14, v142
	v_mul_f32_e32 v15, v15, v143
	s_waitcnt lgkmcnt(0)
	s_nop 1
	v_mfma_f32_32x32x16_bf16 v[0:15], v[96:99], v[112:115], v[0:15]
	ds_read_b128 v[40:43], v89 offset:0
	ds_read_b128 v[44:47], v89 offset:64
	ds_read_b128 v[48:51], v89 offset:128
	ds_read_b128 v[52:55], v89 offset:192
	v_mfma_f32_32x32x16_bf16 v[0:15], v[100:103], v[116:119], v[0:15]
	ds_read_b128 v[128:131], v89 offset:1088
	ds_read_b128 v[132:135], v89 offset:1152
	ds_read_b128 v[136:139], v89 offset:1216
	ds_read_b128 v[140:143], v89 offset:1280
	v_mfma_f32_32x32x16_bf16 v[0:15], v[104:107], v[120:123], v[0:15]
	ds_write_b64 v164, v[16:17] offset:17408
	ds_write_b64 v164, v[18:19] offset:17424
	ds_write_b64 v164, v[20:21] offset:17440
	ds_write_b64 v164, v[22:23] offset:17456
	v_mfma_f32_32x32x16_bf16 v[0:15], v[108:111], v[124:127], v[0:15]
	s_waitcnt lgkmcnt(8)
	v_mfma_f32_16x16x32_bf16 v[24:27], v[40:43], v[56:59], 0
	v_mfma_f32_16x16x32_bf16 v[24:27], v[44:47], v[60:63], v[24:27]
	v_mfma_f32_16x16x32_bf16 v[24:27], v[48:51], v[64:67], v[24:27]
	v_mfma_f32_16x16x32_bf16 v[24:27], v[52:55], v[68:71], v[24:27]
	ds_read_b128 v[40:43], v89 offset:8704
	ds_read_b128 v[44:47], v89 offset:8768
	ds_read_b128 v[48:51], v89 offset:8832
	ds_read_b128 v[52:55], v89 offset:8896
	s_waitcnt lgkmcnt(8)
	v_mfma_f32_16x16x32_bf16 v[28:31], v[128:131], v[56:59], 0
	v_mfma_f32_16x16x32_bf16 v[28:31], v[132:135], v[60:63], v[28:31]
	v_mfma_f32_16x16x32_bf16 v[28:31], v[136:139], v[64:67], v[28:31]
	v_mfma_f32_16x16x32_bf16 v[28:31], v[140:143], v[68:71], v[28:31]
	ds_read_b128 v[128:131], v89 offset:9792
	ds_read_b128 v[132:135], v89 offset:9856
	ds_read_b128 v[136:139], v89 offset:9920
	ds_read_b128 v[140:143], v89 offset:9984
	s_waitcnt lgkmcnt(4)
	v_mfma_f32_16x16x32_bf16 v[32:35], v[40:43], v[56:59], 0
	v_mfma_f32_16x16x32_bf16 v[32:35], v[44:47], v[60:63], v[32:35]
	v_mfma_f32_16x16x32_bf16 v[32:35], v[48:51], v[64:67], v[32:35]
	v_mfma_f32_16x16x32_bf16 v[32:35], v[52:55], v[68:71], v[32:35]
	ds_read_b128 v[72:75], v88 offset:45568
	ds_read_b128 v[76:79], v88 offset:45632
	ds_read_b128 v[80:83], v88 offset:45696
	ds_read_b128 v[84:87], v88 offset:45760
	s_waitcnt lgkmcnt(4)
	v_mfma_f32_16x16x32_bf16 v[36:39], v[128:131], v[56:59], 0
	v_mfma_f32_16x16x32_bf16 v[36:39], v[132:135], v[60:63], v[36:39]
	v_mfma_f32_16x16x32_bf16 v[36:39], v[136:139], v[64:67], v[36:39]
	v_mfma_f32_16x16x32_bf16 v[36:39], v[140:143], v[68:71], v[36:39]
	v_cvt_pk_bf16_f32 v24, v24, v25
	v_cvt_pk_bf16_f32 v25, v26, v27
	v_cvt_pk_bf16_f32 v26, v28, v29
	v_cvt_pk_bf16_f32 v27, v30, v31
	global_store_dwordx4 v90, v[24:27], s[42:43]
	v_cvt_pk_bf16_f32 v32, v32, v33
	v_cvt_pk_bf16_f32 v33, v34, v35
	s_nop 1
	v_cvt_pk_bf16_f32 v34, v36, v37
	v_cvt_pk_bf16_f32 v35, v38, v39
	global_store_dwordx4 v90, v[32:35], s[42:43] offset:64
	s_add_u32 s42, s42, 0x68000
	s_addc_u32 s43, s43, 0
	s_add_i32 s44, s44, 1
	s_waitcnt lgkmcnt(0)
	s_barrier
.Lsc_obody2:
	ds_read_b128 v[128:131], v208 offset:0
	ds_read_b128 v[132:135], v208 offset:32
	ds_read_b128 v[136:139], v208 offset:64
	ds_read_b128 v[140:143], v208 offset:96
	ds_read_b128 v[96:99], v209 offset:0
	ds_read_b128 v[100:103], v209 offset:32
	ds_read_b128 v[104:107], v209 offset:64
	ds_read_b128 v[108:111], v209 offset:96
	ds_read_b128 v[112:115], v210 offset:0
	ds_read_b128 v[116:119], v210 offset:32
	ds_read_b128 v[120:123], v210 offset:64
	ds_read_b128 v[124:127], v210 offset:96
	v_cvt_pk_bf16_f32 v16, v0, v1
	v_cvt_pk_bf16_f32 v17, v2, v3
	v_cvt_pk_bf16_f32 v18, v4, v5
	v_cvt_pk_bf16_f32 v19, v6, v7
	v_cvt_pk_bf16_f32 v20, v8, v9
	v_cvt_pk_bf16_f32 v21, v10, v11
	v_cvt_pk_bf16_f32 v22, v12, v13
	v_cvt_pk_bf16_f32 v23, v14, v15
	s_waitcnt lgkmcnt(8)
	v_mul_f32_e32 v0, v0, v128
	v_mul_f32_e32 v1, v1, v129
	v_mul_f32_e32 v2, v2, v130
	v_mul_f32_e32 v3, v3, v131
	v_mul_f32_e32 v4, v4, v132
	v_mul_f32_e32 v5, v5, v133
	v_mul_f32_e32 v6, v6, v134
	v_mul_f32_e32 v7, v7, v135
	v_mul_f32_e32 v8, v8, v136
	v_mul_f32_e32 v9, v9, v137
	v_mul_f32_e32 v10, v10, v138
	v_mul_f32_e32 v11, v11, v139
	v_mul_f32_e32 v12, v12, v140
	v_mul_f32_e32 v13, v13, v141
	v_mul_f32_e32 v14, v14, v142
	v_mul_f32_e32 v15, v15, v143
	s_waitcnt lgkmcnt(0)
	s_nop 1
	v_mfma_f32_32x32x16_bf16 v[0:15], v[96:99], v[112:115], v[0:15]
	ds_read_b128 v[40:43], v89 offset:17408
	ds_read_b128 v[44:47], v89 offset:17472
	ds_read_b128 v[48:51], v89 offset:17536
	ds_read_b128 v[52:55], v89 offset:17600
	v_mfma_f32_32x32x16_bf16 v[0:15], v[100:103], v[116:119], v[0:15]
	ds_read_b128 v[128:131], v89 offset:18496
	ds_read_b128 v[132:135], v89 offset:18560
	ds_read_b128 v[136:139], v89 offset:18624
	ds_read_b128 v[140:143], v89 offset:18688
	v_mfma_f32_32x32x16_bf16 v[0:15], v[104:107], v[120:123], v[0:15]
	ds_write_b64 v164, v[16:17] offset:0
	ds_write_b64 v164, v[18:19] offset:16
	ds_write_b64 v164, v[20:21] offset:32
	ds_write_b64 v164, v[22:23] offset:48
	v_mfma_f32_32x32x16_bf16 v[0:15], v[108:111], v[124:127], v[0:15]
	s_waitcnt lgkmcnt(8)
	v_mfma_f32_16x16x32_bf16 v[24:27], v[40:43], v[72:75], 0
	v_mfma_f32_16x16x32_bf16 v[24:27], v[44:47], v[76:79], v[24:27]
	v_mfma_f32_16x16x32_bf16 v[24:27], v[48:51], v[80:83], v[24:27]
	v_mfma_f32_16x16x32_bf16 v[24:27], v[52:55], v[84:87], v[24:27]
	ds_read_b128 v[40:43], v89 offset:26112
	ds_read_b128 v[44:47], v89 offset:26176
	ds_read_b128 v[48:51], v89 offset:26240
	ds_read_b128 v[52:55], v89 offset:26304
	s_waitcnt lgkmcnt(8)
	v_mfma_f32_16x16x32_bf16 v[28:31], v[128:131], v[72:75], 0
	v_mfma_f32_16x16x32_bf16 v[28:31], v[132:135], v[76:79], v[28:31]
	v_mfma_f32_16x16x32_bf16 v[28:31], v[136:139], v[80:83], v[28:31]
	v_mfma_f32_16x16x32_bf16 v[28:31], v[140:143], v[84:87], v[28:31]
	ds_read_b128 v[128:131], v89 offset:27200
	ds_read_b128 v[132:135], v89 offset:27264
	ds_read_b128 v[136:139], v89 offset:27328
	ds_read_b128 v[140:143], v89 offset:27392
	s_waitcnt lgkmcnt(4)
	v_mfma_f32_16x16x32_bf16 v[32:35], v[40:43], v[72:75], 0
	v_mfma_f32_16x16x32_bf16 v[32:35], v[44:47], v[76:79], v[32:35]
	v_mfma_f32_16x16x32_bf16 v[32:35], v[48:51], v[80:83], v[32:35]
	v_mfma_f32_16x16x32_bf16 v[32:35], v[52:55], v[84:87], v[32:35]
	ds_read_b128 v[56:59], v88 offset:0
	ds_read_b128 v[60:63], v88 offset:64
	ds_read_b128 v[64:67], v88 offset:128
	ds_read_b128 v[68:71], v88 offset:192
	s_waitcnt lgkmcnt(4)
	v_mfma_f32_16x16x32_bf16 v[36:39], v[128:131], v[72:75], 0
	v_mfma_f32_16x16x32_bf16 v[36:39], v[132:135], v[76:79], v[36:39]
	v_mfma_f32_16x16x32_bf16 v[36:39], v[136:139], v[80:83], v[36:39]
	v_mfma_f32_16x16x32_bf16 v[36:39], v[140:143], v[84:87], v[36:39]
	v_cvt_pk_bf16_f32 v24, v24, v25
	v_cvt_pk_bf16_f32 v25, v26, v27
	v_cvt_pk_bf16_f32 v26, v28, v29
	v_cvt_pk_bf16_f32 v27, v30, v31
	global_store_dwordx4 v90, v[24:27], s[42:43]
	v_cvt_pk_bf16_f32 v32, v32, v33
	v_cvt_pk_bf16_f32 v33, v34, v35
	s_nop 1
	v_cvt_pk_bf16_f32 v34, v36, v37
	v_cvt_pk_bf16_f32 v35, v38, v39
	global_store_dwordx4 v90, v[32:35], s[42:43] offset:64
	s_add_u32 s42, s42, 0x68000
	s_addc_u32 s43, s43, 0
	s_add_i32 s44, s44, 1
	s_waitcnt lgkmcnt(0)
	s_barrier
.Lsc_obody3:
	ds_read_b128 v[128:131], v208 offset:45568
	ds_read_b128 v[132:135], v208 offset:45600
	ds_read_b128 v[136:139], v208 offset:45632
	ds_read_b128 v[140:143], v208 offset:45664
	ds_read_b128 v[96:99], v209 offset:45568
	ds_read_b128 v[100:103], v209 offset:45600
	ds_read_b128 v[104:107], v209 offset:45632
	ds_read_b128 v[108:111], v209 offset:45664
	ds_read_b128 v[112:115], v210 offset:45568
	ds_read_b128 v[116:119], v210 offset:45600
	ds_read_b128 v[120:123], v210 offset:45632
	ds_read_b128 v[124:127], v210 offset:45664
	v_cvt_pk_bf16_f32 v16, v0, v1
	v_cvt_pk_bf16_f32 v17, v2, v3
	v_cvt_pk_bf16_f32 v18, v4, v5
	v_cvt_pk_bf16_f32 v19, v6, v7
	v_cvt_pk_bf16_f32 v20, v8, v9
	v_cvt_pk_bf16_f32 v21, v10, v11
	v_cvt_pk_bf16_f32 v22, v12, v13
	v_cvt_pk_bf16_f32 v23, v14, v15
	s_waitcnt lgkmcnt(8)
	v_mul_f32_e32 v0, v0, v128
	v_mul_f32_e32 v1, v1, v129
	v_mul_f32_e32 v2, v2, v130
	v_mul_f32_e32 v3, v3, v131
	v_mul_f32_e32 v4, v4, v132
	v_mul_f32_e32 v5, v5, v133
	v_mul_f32_e32 v6, v6, v134
	v_mul_f32_e32 v7, v7, v135
	v_mul_f32_e32 v8, v8, v136
	v_mul_f32_e32 v9, v9, v137
	v_mul_f32_e32 v10, v10, v138
	v_mul_f32_e32 v11, v11, v139
	v_mul_f32_e32 v12, v12, v140
	v_mul_f32_e32 v13, v13, v141
	v_mul_f32_e32 v14, v14, v142
	v_mul_f32_e32 v15, v15, v143
	s_waitcnt lgkmcnt(0)
	s_nop 1
	v_mfma_f32_32x32x16_bf16 v[0:15], v[96:99], v[112:115], v[0:15]
	ds_read_b128 v[40:43], v89 offset:0
	ds_read_b128 v[44:47], v89 offset:64
	ds_read_b128 v[48:51], v89 offset:128
	ds_read_b128 v[52:55], v89 offset:192
	v_mfma_f32_32x32x16_bf16 v[0:15], v[100:103], v[116:119], v[0:15]
	ds_read_b128 v[128:131], v89 offset:1088
	ds_read_b128 v[132:135], v89 offset:1152
	ds_read_b128 v[136:139], v89 offset:1216
	ds_read_b128 v[140:143], v89 offset:1280
	v_mfma_f32_32x32x16_bf16 v[0:15], v[104:107], v[120:123], v[0:15]
	ds_write_b64 v164, v[16:17] offset:17408
	ds_write_b64 v164, v[18:19] offset:17424
	ds_write_b64 v164, v[20:21] offset:17440
	ds_write_b64 v164, v[22:23] offset:17456
	v_mfma_f32_32x32x16_bf16 v[0:15], v[108:111], v[124:127], v[0:15]
	s_waitcnt lgkmcnt(8)
	v_mfma_f32_16x16x32_bf16 v[24:27], v[40:43], v[56:59], 0
	v_mfma_f32_16x16x32_bf16 v[24:27], v[44:47], v[60:63], v[24:27]
	v_mfma_f32_16x16x32_bf16 v[24:27], v[48:51], v[64:67], v[24:27]
	v_mfma_f32_16x16x32_bf16 v[24:27], v[52:55], v[68:71], v[24:27]
	ds_read_b128 v[40:43], v89 offset:8704
	ds_read_b128 v[44:47], v89 offset:8768
	ds_read_b128 v[48:51], v89 offset:8832
	ds_read_b128 v[52:55], v89 offset:8896
	s_waitcnt lgkmcnt(8)
	v_mfma_f32_16x16x32_bf16 v[28:31], v[128:131], v[56:59], 0
	v_mfma_f32_16x16x32_bf16 v[28:31], v[132:135], v[60:63], v[28:31]
	v_mfma_f32_16x16x32_bf16 v[28:31], v[136:139], v[64:67], v[28:31]
	v_mfma_f32_16x16x32_bf16 v[28:31], v[140:143], v[68:71], v[28:31]
	ds_read_b128 v[128:131], v89 offset:9792
	ds_read_b128 v[132:135], v89 offset:9856
	ds_read_b128 v[136:139], v89 offset:9920
	ds_read_b128 v[140:143], v89 offset:9984
	s_waitcnt lgkmcnt(4)
	v_mfma_f32_16x16x32_bf16 v[32:35], v[40:43], v[56:59], 0
	v_mfma_f32_16x16x32_bf16 v[32:35], v[44:47], v[60:63], v[32:35]
	v_mfma_f32_16x16x32_bf16 v[32:35], v[48:51], v[64:67], v[32:35]
	v_mfma_f32_16x16x32_bf16 v[32:35], v[52:55], v[68:71], v[32:35]
	ds_read_b128 v[72:75], v88 offset:45568
	ds_read_b128 v[76:79], v88 offset:45632
	ds_read_b128 v[80:83], v88 offset:45696
	ds_read_b128 v[84:87], v88 offset:45760
	s_waitcnt lgkmcnt(4)
	v_mfma_f32_16x16x32_bf16 v[36:39], v[128:131], v[56:59], 0
	v_mfma_f32_16x16x32_bf16 v[36:39], v[132:135], v[60:63], v[36:39]
	v_mfma_f32_16x16x32_bf16 v[36:39], v[136:139], v[64:67], v[36:39]
	v_mfma_f32_16x16x32_bf16 v[36:39], v[140:143], v[68:71], v[36:39]
	v_cvt_pk_bf16_f32 v24, v24, v25
	v_cvt_pk_bf16_f32 v25, v26, v27
	v_cvt_pk_bf16_f32 v26, v28, v29
	v_cvt_pk_bf16_f32 v27, v30, v31
	global_store_dwordx4 v90, v[24:27], s[42:43]
	v_cvt_pk_bf16_f32 v32, v32, v33
	v_cvt_pk_bf16_f32 v33, v34, v35
	s_nop 1
	v_cvt_pk_bf16_f32 v34, v36, v37
	v_cvt_pk_bf16_f32 v35, v38, v39
	global_store_dwordx4 v90, v[32:35], s[42:43] offset:64
	s_add_u32 s42, s42, 0x68000
	s_addc_u32 s43, s43, 0
	s_add_i32 s44, s44, 1
	s_waitcnt lgkmcnt(0)
	s_barrier
	s_cmp_eq_u32 s44, 64
	s_cbranch_scc1 .Lsc_oepi

.Lsc_obody5:
	ds_read_b128 v[128:131], v208 offset:45568
	ds_read_b128 v[132:135], v208 offset:45600
	ds_read_b128 v[136:139], v208 offset:45632
	ds_read_b128 v[140:143], v208 offset:45664
	ds_read_b128 v[96:99], v209 offset:45568
	ds_read_b128 v[100:103], v209 offset:45600
	ds_read_b128 v[104:107], v209 offset:45632
	ds_read_b128 v[108:111], v209 offset:45664
	ds_read_b128 v[112:115], v210 offset:45568
	ds_read_b128 v[116:119], v210 offset:45600
	ds_read_b128 v[120:123], v210 offset:45632
	ds_read_b128 v[124:127], v210 offset:45664
	v_cvt_pk_bf16_f32 v16, v0, v1
	v_cvt_pk_bf16_f32 v17, v2, v3
	v_cvt_pk_bf16_f32 v18, v4, v5
	v_cvt_pk_bf16_f32 v19, v6, v7
	v_cvt_pk_bf16_f32 v20, v8, v9
	v_cvt_pk_bf16_f32 v21, v10, v11
	v_cvt_pk_bf16_f32 v22, v12, v13
	v_cvt_pk_bf16_f32 v23, v14, v15
	s_waitcnt lgkmcnt(8)
	v_mul_f32_e32 v0, v0, v128
	v_mul_f32_e32 v1, v1, v129
	v_mul_f32_e32 v2, v2, v130
	v_mul_f32_e32 v3, v3, v131
	v_mul_f32_e32 v4, v4, v132
	v_mul_f32_e32 v5, v5, v133
	v_mul_f32_e32 v6, v6, v134
	v_mul_f32_e32 v7, v7, v135
	v_mul_f32_e32 v8, v8, v136
	v_mul_f32_e32 v9, v9, v137
	v_mul_f32_e32 v10, v10, v138
	v_mul_f32_e32 v11, v11, v139
	v_mul_f32_e32 v12, v12, v140
	v_mul_f32_e32 v13, v13, v141
	v_mul_f32_e32 v14, v14, v142
	v_mul_f32_e32 v15, v15, v143
	s_waitcnt lgkmcnt(0)
	s_nop 1
	v_mfma_f32_32x32x16_bf16 v[0:15], v[96:99], v[112:115], v[0:15]
	ds_read_b128 v[40:43], v89 offset:0
	ds_read_b128 v[44:47], v89 offset:64
	ds_read_b128 v[48:51], v89 offset:128
	ds_read_b128 v[52:55], v89 offset:192
	v_mfma_f32_32x32x16_bf16 v[0:15], v[100:103], v[116:119], v[0:15]
	ds_read_b128 v[128:131], v89 offset:1088
	ds_read_b128 v[132:135], v89 offset:1152
	ds_read_b128 v[136:139], v89 offset:1216
	ds_read_b128 v[140:143], v89 offset:1280
	v_mfma_f32_32x32x16_bf16 v[0:15], v[104:107], v[120:123], v[0:15]
	ds_write_b64 v164, v[16:17] offset:17408
	ds_write_b64 v164, v[18:19] offset:17424
	ds_write_b64 v164, v[20:21] offset:17440
	ds_write_b64 v164, v[22:23] offset:17456
	v_mfma_f32_32x32x16_bf16 v[0:15], v[108:111], v[124:127], v[0:15]
	s_waitcnt lgkmcnt(8)
	v_mfma_f32_16x16x32_bf16 v[24:27], v[40:43], v[56:59], 0
	v_mfma_f32_16x16x32_bf16 v[24:27], v[44:47], v[60:63], v[24:27]
	v_mfma_f32_16x16x32_bf16 v[24:27], v[48:51], v[64:67], v[24:27]
	v_mfma_f32_16x16x32_bf16 v[24:27], v[52:55], v[68:71], v[24:27]
	ds_read_b128 v[40:43], v89 offset:8704
	ds_read_b128 v[44:47], v89 offset:8768
	ds_read_b128 v[48:51], v89 offset:8832
	ds_read_b128 v[52:55], v89 offset:8896
	s_waitcnt lgkmcnt(8)
	v_mfma_f32_16x16x32_bf16 v[28:31], v[128:131], v[56:59], 0
	v_mfma_f32_16x16x32_bf16 v[28:31], v[132:135], v[60:63], v[28:31]
	v_mfma_f32_16x16x32_bf16 v[28:31], v[136:139], v[64:67], v[28:31]
	v_mfma_f32_16x16x32_bf16 v[28:31], v[140:143], v[68:71], v[28:31]
	ds_read_b128 v[128:131], v89 offset:9792
	ds_read_b128 v[132:135], v89 offset:9856
	ds_read_b128 v[136:139], v89 offset:9920
	ds_read_b128 v[140:143], v89 offset:9984
	s_waitcnt lgkmcnt(4)
	v_mfma_f32_16x16x32_bf16 v[32:35], v[40:43], v[56:59], 0
	v_mfma_f32_16x16x32_bf16 v[32:35], v[44:47], v[60:63], v[32:35]
	v_mfma_f32_16x16x32_bf16 v[32:35], v[48:51], v[64:67], v[32:35]
	v_mfma_f32_16x16x32_bf16 v[32:35], v[52:55], v[68:71], v[32:35]
	ds_read_b128 v[72:75], v88 offset:45568
	ds_read_b128 v[76:79], v88 offset:45632
	ds_read_b128 v[80:83], v88 offset:45696
	ds_read_b128 v[84:87], v88 offset:45760
	s_waitcnt lgkmcnt(4)
	v_mfma_f32_16x16x32_bf16 v[36:39], v[128:131], v[56:59], 0
	v_mfma_f32_16x16x32_bf16 v[36:39], v[132:135], v[60:63], v[36:39]
	v_mfma_f32_16x16x32_bf16 v[36:39], v[136:139], v[64:67], v[36:39]
	v_mfma_f32_16x16x32_bf16 v[36:39], v[140:143], v[68:71], v[36:39]
	v_cvt_pk_bf16_f32 v24, v24, v25
	v_cvt_pk_bf16_f32 v25, v26, v27
	v_cvt_pk_bf16_f32 v26, v28, v29
	v_cvt_pk_bf16_f32 v27, v30, v31
	global_store_dwordx4 v90, v[24:27], s[42:43]
	v_cvt_pk_bf16_f32 v32, v32, v33
	v_cvt_pk_bf16_f32 v33, v34, v35
	s_nop 1
	v_cvt_pk_bf16_f32 v34, v36, v37
	v_cvt_pk_bf16_f32 v35, v38, v39
	global_store_dwordx4 v90, v[32:35], s[42:43] offset:64
	s_add_u32 s42, s42, 0x68000
	s_addc_u32 s43, s43, 0
	s_add_i32 s44, s44, 1
	s_waitcnt lgkmcnt(0)
	s_barrier
	s_branch .Lsc_oloop
